# FFN gate/up GEMM K-loop: one A-tile LDS-DMA stage moved from phase 2 to phase 3 (DMA pieces per phase 2/4/4/6 instead of 2/6/2/6), phase-2 vmcnt 8->6
# baseline (speedup 1.0000x reference)
.LBB0_920:
	s_add_u32 s28, s46, 0xfff80080
	s_addc_u32 s29, s47, -1
	s_add_i32 s91, 0, 0x10000
	s_cmp_eq_u32 s90, 28
	s_cselect_b32 s49, s27, s29
	s_cselect_b32 s48, s86, s28
	s_cselect_b32 s29, s23, s89
	s_cselect_b32 s28, s87, s88
	s_add_i32 s94, 0, 0x14000
	v_add_u32_e32 v156, s91, v141
	v_add_u32_e32 v172, s94, v141
	ds_read_b128 v[144:147], v156
	ds_read_b128 v[148:151], v156 offset:1024
	ds_read_b128 v[152:155], v156 offset:2048
	ds_read_b128 v[156:159], v156 offset:3072
	ds_read_b128 v[160:163], v172
	ds_read_b128 v[164:167], v172 offset:1024
	ds_read_b128 v[168:171], v172 offset:2048
	ds_read_b128 v[172:175], v172 offset:3072
	s_add_i32 m0, s45, 0xc000
	ds_read_b128 v[176:179], v143
	ds_read_b128 v[180:183], v143 offset:1024
	ds_read_b128 v[184:187], v143 offset:2048
	ds_read_b128 v[188:191], v143 offset:3072
	ds_read_b128 v[192:195], v143 offset:4096
	ds_read_b128 v[196:199], v143 offset:5120
	ds_read_b128 v[200:203], v143 offset:6144
	ds_read_b128 v[204:207], v143 offset:7168
	global_load_lds_dwordx4 v136, s[46:47]
	s_add_i32 m0, s45, 0xe000
	s_nop 0
	global_load_lds_dwordx4 v138, s[46:47]
	s_waitcnt vmcnt(8)
	s_waitcnt lgkmcnt(0)
	s_barrier
	s_setprio 1
	s_waitcnt lgkmcnt(0)
	v_mfma_f32_16x16x32_bf16 v[126:129], v[144:147], v[176:179], v[126:129]
	v_mfma_f32_16x16x32_bf16 v[118:121], v[152:155], v[176:179], v[118:121]
	v_mfma_f32_16x16x32_bf16 v[110:113], v[144:147], v[184:187], v[110:113]
	v_mfma_f32_16x16x32_bf16 v[102:105], v[152:155], v[184:187], v[102:105]
	v_mfma_f32_16x16x32_bf16 v[94:97], v[144:147], v[192:195], v[94:97]
	v_mfma_f32_16x16x32_bf16 v[86:89], v[152:155], v[192:195], v[86:89]
	v_mfma_f32_16x16x32_bf16 v[78:81], v[144:147], v[200:203], v[78:81]
	v_mfma_f32_16x16x32_bf16 v[70:73], v[152:155], v[200:203], v[70:73]
	v_mfma_f32_16x16x32_bf16 v[126:129], v[148:151], v[180:183], v[126:129]
	v_mfma_f32_16x16x32_bf16 v[118:121], v[156:159], v[180:183], v[118:121]
	v_mfma_f32_16x16x32_bf16 v[110:113], v[148:151], v[188:191], v[110:113]
	v_mfma_f32_16x16x32_bf16 v[102:105], v[156:159], v[188:191], v[102:105]
	v_mfma_f32_16x16x32_bf16 v[94:97], v[148:151], v[196:199], v[94:97]
	v_mfma_f32_16x16x32_bf16 v[86:89], v[156:159], v[196:199], v[86:89]
	v_mfma_f32_16x16x32_bf16 v[78:81], v[148:151], v[204:207], v[78:81]
	v_mfma_f32_16x16x32_bf16 v[70:73], v[156:159], v[204:207], v[70:73]
	s_setprio 0
	s_setprio 1
	v_mfma_f32_16x16x32_bf16 v[122:125], v[160:163], v[176:179], v[122:125]
	v_mfma_f32_16x16x32_bf16 v[114:117], v[168:171], v[176:179], v[114:117]
	v_mfma_f32_16x16x32_bf16 v[106:109], v[160:163], v[184:187], v[106:109]
	v_mfma_f32_16x16x32_bf16 v[98:101], v[168:171], v[184:187], v[98:101]
	v_mfma_f32_16x16x32_bf16 v[90:93], v[160:163], v[192:195], v[90:93]
	v_mfma_f32_16x16x32_bf16 v[82:85], v[168:171], v[192:195], v[82:85]
	v_mfma_f32_16x16x32_bf16 v[74:77], v[160:163], v[200:203], v[74:77]
	v_mfma_f32_16x16x32_bf16 v[66:69], v[168:171], v[200:203], v[66:69]
	v_mfma_f32_16x16x32_bf16 v[122:125], v[164:167], v[180:183], v[122:125]
	v_mfma_f32_16x16x32_bf16 v[114:117], v[172:175], v[180:183], v[114:117]
	v_mfma_f32_16x16x32_bf16 v[106:109], v[164:167], v[188:191], v[106:109]
	v_mfma_f32_16x16x32_bf16 v[98:101], v[172:175], v[188:191], v[98:101]
	v_mfma_f32_16x16x32_bf16 v[90:93], v[164:167], v[196:199], v[90:93]
	v_mfma_f32_16x16x32_bf16 v[82:85], v[172:175], v[196:199], v[82:85]
	v_mfma_f32_16x16x32_bf16 v[74:77], v[164:167], v[204:207], v[74:77]
	v_mfma_f32_16x16x32_bf16 v[66:69], v[172:175], v[204:207], v[66:69]
	s_setprio 0
	s_barrier
	s_add_i32 s91, s91, s37
	s_mov_b32 m0, s91
	ds_read_b128 v[176:179], v143 offset:16384
	ds_read_b128 v[180:183], v143 offset:17408
	ds_read_b128 v[184:187], v143 offset:18432
	ds_read_b128 v[188:191], v143 offset:19456
	ds_read_b128 v[192:195], v143 offset:20480
	ds_read_b128 v[196:199], v143 offset:21504
	ds_read_b128 v[200:203], v143 offset:22528
	ds_read_b128 v[204:207], v143 offset:23552
	global_load_lds_dwordx4 v16, s[28:29]
	s_add_i32 m0, s91, 0x2000
	s_add_u32 s92, s28, 0x80000
	s_addc_u32 s93, s29, 0
	s_add_i32 s91, s94, s37
	global_load_lds_dwordx4 v130, s[28:29]
	s_mov_b32 m0, s91
	v_lshl_add_u64 v[228:229], s[48:49], 0, v[132:133]
	global_load_lds_dwordx4 v16, s[92:93]
	s_add_i32 m0, s91, 0x2000
	s_nop 0
	global_load_lds_dwordx4 v130, s[92:93]
	s_waitcnt vmcnt(6)
	s_waitcnt lgkmcnt(0)
	s_barrier
	s_setprio 1
	s_waitcnt lgkmcnt(0)
	v_mfma_f32_16x16x32_bf16 v[62:65], v[144:147], v[176:179], v[62:65]
	v_mfma_f32_16x16x32_bf16 v[54:57], v[152:155], v[176:179], v[54:57]
	v_mfma_f32_16x16x32_bf16 v[46:49], v[144:147], v[184:187], v[46:49]
	v_mfma_f32_16x16x32_bf16 v[38:41], v[152:155], v[184:187], v[38:41]
	v_mfma_f32_16x16x32_bf16 v[30:33], v[144:147], v[192:195], v[30:33]
	v_mfma_f32_16x16x32_bf16 v[22:25], v[152:155], v[192:195], v[22:25]
	v_mfma_f32_16x16x32_bf16 v[12:15], v[144:147], v[200:203], v[12:15]
	v_mfma_f32_16x16x32_bf16 v[4:7], v[152:155], v[200:203], v[4:7]
	v_mfma_f32_16x16x32_bf16 v[62:65], v[148:151], v[180:183], v[62:65]
	v_mfma_f32_16x16x32_bf16 v[54:57], v[156:159], v[180:183], v[54:57]
	v_mfma_f32_16x16x32_bf16 v[46:49], v[148:151], v[188:191], v[46:49]
	v_mfma_f32_16x16x32_bf16 v[38:41], v[156:159], v[188:191], v[38:41]
	v_mfma_f32_16x16x32_bf16 v[30:33], v[148:151], v[196:199], v[30:33]
	v_mfma_f32_16x16x32_bf16 v[22:25], v[156:159], v[196:199], v[22:25]
	v_mfma_f32_16x16x32_bf16 v[12:15], v[148:151], v[204:207], v[12:15]
	v_mfma_f32_16x16x32_bf16 v[4:7], v[156:159], v[204:207], v[4:7]
	s_setprio 0
	s_setprio 1
	v_mfma_f32_16x16x32_bf16 v[58:61], v[160:163], v[176:179], v[58:61]
	v_mfma_f32_16x16x32_bf16 v[50:53], v[168:171], v[176:179], v[50:53]
	v_mfma_f32_16x16x32_bf16 v[42:45], v[160:163], v[184:187], v[42:45]
	v_mfma_f32_16x16x32_bf16 v[34:37], v[168:171], v[184:187], v[34:37]
	v_mfma_f32_16x16x32_bf16 v[26:29], v[160:163], v[192:195], v[26:29]
	v_mfma_f32_16x16x32_bf16 v[18:21], v[168:171], v[192:195], v[18:21]
	v_mfma_f32_16x16x32_bf16 v[8:11], v[160:163], v[200:203], v[8:11]
	v_mfma_f32_16x16x32_bf16 v[0:3], v[168:171], v[200:203], v[0:3]
	v_mfma_f32_16x16x32_bf16 v[58:61], v[164:167], v[180:183], v[58:61]
	v_mfma_f32_16x16x32_bf16 v[50:53], v[172:175], v[180:183], v[50:53]
	v_mfma_f32_16x16x32_bf16 v[42:45], v[164:167], v[188:191], v[42:45]
	v_mfma_f32_16x16x32_bf16 v[34:37], v[172:175], v[188:191], v[34:37]
	v_mfma_f32_16x16x32_bf16 v[26:29], v[164:167], v[196:199], v[26:29]
	v_mfma_f32_16x16x32_bf16 v[18:21], v[172:175], v[196:199], v[18:21]
	v_mfma_f32_16x16x32_bf16 v[8:11], v[164:167], v[204:207], v[8:11]
	v_mfma_f32_16x16x32_bf16 v[0:3], v[172:175], v[204:207], v[0:3]
	s_setprio 0
	s_barrier
	v_lshl_add_u64 v[226:227], s[48:49], 0, v[134:135]
	s_mov_b32 m0, s45
	s_nop 0
	global_load_lds_dwordx4 v[226:227], off
	s_mov_b32 m0, s53
	s_nop 0
	global_load_lds_dwordx4 v[228:229], off
	s_add_i32 s91, 0, 0x18000
	s_add_i32 s92, 0, 0x1c000
	v_add_u32_e32 v156, s91, v141
	v_add_u32_e32 v172, s92, v141
	ds_read_b128 v[144:147], v156
	ds_read_b128 v[148:151], v156 offset:1024
	ds_read_b128 v[152:155], v156 offset:2048
	ds_read_b128 v[156:159], v156 offset:3072
	ds_read_b128 v[160:163], v172
	ds_read_b128 v[164:167], v172 offset:1024
	ds_read_b128 v[168:171], v172 offset:2048
	ds_read_b128 v[172:175], v172 offset:3072
	s_add_u32 s48, s48, 0x80000
	s_addc_u32 s49, s49, 0
	s_mov_b32 m0, s57
	ds_read_b128 v[176:179], v143 offset:32768
	ds_read_b128 v[180:183], v143 offset:33792
	ds_read_b128 v[184:187], v143 offset:34816
	ds_read_b128 v[188:191], v143 offset:35840
	ds_read_b128 v[192:195], v143 offset:36864
	ds_read_b128 v[196:199], v143 offset:37888
	ds_read_b128 v[200:203], v143 offset:38912
	ds_read_b128 v[204:207], v143 offset:39936
	global_load_lds_dwordx4 v134, s[48:49]
	s_mov_b32 m0, s58
	s_nop 0
	global_load_lds_dwordx4 v132, s[48:49]
	s_waitcnt vmcnt(8)
	s_waitcnt lgkmcnt(0)
	s_barrier
	s_setprio 1
	s_waitcnt lgkmcnt(0)
	v_mfma_f32_16x16x32_bf16 v[126:129], v[144:147], v[176:179], v[126:129]
	v_mfma_f32_16x16x32_bf16 v[118:121], v[152:155], v[176:179], v[118:121]
	v_mfma_f32_16x16x32_bf16 v[110:113], v[144:147], v[184:187], v[110:113]
	v_mfma_f32_16x16x32_bf16 v[102:105], v[152:155], v[184:187], v[102:105]
	v_mfma_f32_16x16x32_bf16 v[94:97], v[144:147], v[192:195], v[94:97]
	v_mfma_f32_16x16x32_bf16 v[86:89], v[152:155], v[192:195], v[86:89]
	v_mfma_f32_16x16x32_bf16 v[78:81], v[144:147], v[200:203], v[78:81]
	v_mfma_f32_16x16x32_bf16 v[70:73], v[152:155], v[200:203], v[70:73]
	v_mfma_f32_16x16x32_bf16 v[126:129], v[148:151], v[180:183], v[126:129]
	v_mfma_f32_16x16x32_bf16 v[118:121], v[156:159], v[180:183], v[118:121]
	v_mfma_f32_16x16x32_bf16 v[110:113], v[148:151], v[188:191], v[110:113]
	v_mfma_f32_16x16x32_bf16 v[102:105], v[156:159], v[188:191], v[102:105]
	v_mfma_f32_16x16x32_bf16 v[94:97], v[148:151], v[196:199], v[94:97]
	v_mfma_f32_16x16x32_bf16 v[86:89], v[156:159], v[196:199], v[86:89]
	v_mfma_f32_16x16x32_bf16 v[78:81], v[148:151], v[204:207], v[78:81]
	v_mfma_f32_16x16x32_bf16 v[70:73], v[156:159], v[204:207], v[70:73]
	s_setprio 0
	s_setprio 1
	v_mfma_f32_16x16x32_bf16 v[122:125], v[160:163], v[176:179], v[122:125]
	v_mfma_f32_16x16x32_bf16 v[114:117], v[168:171], v[176:179], v[114:117]
	v_mfma_f32_16x16x32_bf16 v[106:109], v[160:163], v[184:187], v[106:109]
	v_mfma_f32_16x16x32_bf16 v[98:101], v[168:171], v[184:187], v[98:101]
	v_mfma_f32_16x16x32_bf16 v[90:93], v[160:163], v[192:195], v[90:93]
	v_mfma_f32_16x16x32_bf16 v[82:85], v[168:171], v[192:195], v[82:85]
	v_mfma_f32_16x16x32_bf16 v[74:77], v[160:163], v[200:203], v[74:77]
	v_mfma_f32_16x16x32_bf16 v[66:69], v[168:171], v[200:203], v[66:69]
	v_mfma_f32_16x16x32_bf16 v[122:125], v[164:167], v[180:183], v[122:125]
	v_mfma_f32_16x16x32_bf16 v[114:117], v[172:175], v[180:183], v[114:117]
	v_mfma_f32_16x16x32_bf16 v[106:109], v[164:167], v[188:191], v[106:109]
	v_mfma_f32_16x16x32_bf16 v[98:101], v[172:175], v[188:191], v[98:101]
	v_mfma_f32_16x16x32_bf16 v[90:93], v[164:167], v[196:199], v[90:93]
	v_mfma_f32_16x16x32_bf16 v[82:85], v[172:175], v[196:199], v[82:85]
	v_mfma_f32_16x16x32_bf16 v[74:77], v[164:167], v[204:207], v[74:77]
	v_mfma_f32_16x16x32_bf16 v[66:69], v[172:175], v[204:207], v[66:69]
	s_setprio 0
	s_barrier
	s_add_i32 s48, s91, s37
	s_add_u32 s28, s28, 0x80
	s_addc_u32 s29, s29, 0
	s_mov_b32 m0, s48
	ds_read_b128 v[176:179], v143 offset:49152
	ds_read_b128 v[180:183], v143 offset:50176
	ds_read_b128 v[184:187], v143 offset:51200
	ds_read_b128 v[188:191], v143 offset:52224
	ds_read_b128 v[192:195], v143 offset:53248
	ds_read_b128 v[196:199], v143 offset:54272
	ds_read_b128 v[200:203], v143 offset:55296
	ds_read_b128 v[204:207], v143 offset:56320
	global_load_lds_dwordx4 v16, s[28:29]
	s_add_i32 m0, s48, 0x2000
	s_add_i32 s48, s92, s37
	global_load_lds_dwordx4 v130, s[28:29]
	s_add_u32 s28, s28, 0x80000
	s_addc_u32 s29, s29, 0
	s_mov_b32 m0, s48
	s_nop 0
	global_load_lds_dwordx4 v16, s[28:29]
	s_add_i32 m0, s48, 0x2000
	s_nop 0
	global_load_lds_dwordx4 v130, s[28:29]
	v_lshl_add_u64 v[216:217], v[226:227], 0, s[34:35]
	s_mov_b32 m0, s59
	s_nop 0
	global_load_lds_dwordx4 v[216:217], off
	v_lshl_add_u64 v[216:217], v[228:229], 0, s[34:35]
	s_mov_b32 m0, s83
	s_nop 0
	global_load_lds_dwordx4 v[216:217], off
	s_waitcnt vmcnt(8)
	s_waitcnt lgkmcnt(0)
	s_barrier
	s_setprio 1
	s_waitcnt lgkmcnt(0)
	v_mfma_f32_16x16x32_bf16 v[62:65], v[144:147], v[176:179], v[62:65]
	v_mfma_f32_16x16x32_bf16 v[54:57], v[152:155], v[176:179], v[54:57]
	v_mfma_f32_16x16x32_bf16 v[46:49], v[144:147], v[184:187], v[46:49]
	v_mfma_f32_16x16x32_bf16 v[38:41], v[152:155], v[184:187], v[38:41]
	v_mfma_f32_16x16x32_bf16 v[30:33], v[144:147], v[192:195], v[30:33]
	v_mfma_f32_16x16x32_bf16 v[22:25], v[152:155], v[192:195], v[22:25]
	v_mfma_f32_16x16x32_bf16 v[12:15], v[144:147], v[200:203], v[12:15]
	v_mfma_f32_16x16x32_bf16 v[4:7], v[152:155], v[200:203], v[4:7]
	v_mfma_f32_16x16x32_bf16 v[62:65], v[148:151], v[180:183], v[62:65]
	v_mfma_f32_16x16x32_bf16 v[54:57], v[156:159], v[180:183], v[54:57]
	v_mfma_f32_16x16x32_bf16 v[46:49], v[148:151], v[188:191], v[46:49]
	v_mfma_f32_16x16x32_bf16 v[38:41], v[156:159], v[188:191], v[38:41]
	v_mfma_f32_16x16x32_bf16 v[30:33], v[148:151], v[196:199], v[30:33]
	v_mfma_f32_16x16x32_bf16 v[22:25], v[156:159], v[196:199], v[22:25]
	v_mfma_f32_16x16x32_bf16 v[12:15], v[148:151], v[204:207], v[12:15]
	v_mfma_f32_16x16x32_bf16 v[4:7], v[156:159], v[204:207], v[4:7]
	s_setprio 0
	s_setprio 1
	v_mfma_f32_16x16x32_bf16 v[58:61], v[160:163], v[176:179], v[58:61]
	v_mfma_f32_16x16x32_bf16 v[50:53], v[168:171], v[176:179], v[50:53]
	v_mfma_f32_16x16x32_bf16 v[42:45], v[160:163], v[184:187], v[42:45]
	v_mfma_f32_16x16x32_bf16 v[34:37], v[168:171], v[184:187], v[34:37]
	v_mfma_f32_16x16x32_bf16 v[26:29], v[160:163], v[192:195], v[26:29]
	v_mfma_f32_16x16x32_bf16 v[18:21], v[168:171], v[192:195], v[18:21]
	v_mfma_f32_16x16x32_bf16 v[8:11], v[160:163], v[200:203], v[8:11]
	v_mfma_f32_16x16x32_bf16 v[0:3], v[168:171], v[200:203], v[0:3]
	v_mfma_f32_16x16x32_bf16 v[58:61], v[164:167], v[180:183], v[58:61]
	v_mfma_f32_16x16x32_bf16 v[50:53], v[172:175], v[180:183], v[50:53]
	v_mfma_f32_16x16x32_bf16 v[42:45], v[164:167], v[188:191], v[42:45]
	v_mfma_f32_16x16x32_bf16 v[34:37], v[172:175], v[188:191], v[34:37]
	v_mfma_f32_16x16x32_bf16 v[26:29], v[164:167], v[196:199], v[26:29]
	v_mfma_f32_16x16x32_bf16 v[18:21], v[172:175], v[196:199], v[18:21]
	v_mfma_f32_16x16x32_bf16 v[8:11], v[164:167], v[204:207], v[8:11]
	v_mfma_f32_16x16x32_bf16 v[0:3], v[172:175], v[204:207], v[0:3]
	s_setprio 0
	s_barrier
	s_add_i32 s90, s90, 2
	s_add_u32 s46, s46, 0x100
	s_addc_u32 s47, s47, 0
	s_add_u32 s88, s88, 0x100
	s_addc_u32 s89, s89, 0
	s_cmp_gt_u32 s90, 29
	s_cbranch_scc0 .LBB0_920
	s_and_b64 vcc, exec, s[18:19]
	s_cbranch_vccz .LBB0_923
	s_barrier
